# v22 + prologue transposes: 32 loads of an item in flight (inner loop fully unrolled, counted waits)
# speedup vs baseline: 1.0059x; 1.0059x over previous
.LBB0_31:
	v_lshl_add_u64 v[70:71], v[54:55], 0, s[10:11]
	v_lshl_add_u64 v[72:73], v[52:53], 0, s[10:11]
	v_lshl_add_u64 v[74:75], v[50:51], 0, s[10:11]
	v_lshl_add_u64 v[76:77], v[48:49], 0, s[10:11]
	v_lshl_add_u64 v[78:79], v[46:47], 0, s[10:11]
	v_lshl_add_u64 v[80:81], v[44:45], 0, s[10:11]
	v_lshl_add_u64 v[82:83], v[42:43], 0, s[10:11]
	v_lshl_add_u64 v[84:85], v[40:41], 0, s[10:11]
	global_load_dword v93, v[70:71], off nt
	global_load_dword v94, v[72:73], off nt
	global_load_dword v95, v[74:75], off nt
	global_load_dword v96, v[76:77], off nt
	global_load_dword v97, v[78:79], off nt
	global_load_dword v98, v[80:81], off nt
	global_load_dword v99, v[82:83], off nt
	global_load_dword v100, v[84:85], off nt
	s_add_u32 s10, s10, 0x20000
	s_addc_u32 s11, s11, 0
	v_lshl_add_u64 v[70:71], v[54:55], 0, s[10:11]
	v_lshl_add_u64 v[72:73], v[52:53], 0, s[10:11]
	v_lshl_add_u64 v[74:75], v[50:51], 0, s[10:11]
	v_lshl_add_u64 v[76:77], v[48:49], 0, s[10:11]
	v_lshl_add_u64 v[78:79], v[46:47], 0, s[10:11]
	v_lshl_add_u64 v[80:81], v[44:45], 0, s[10:11]
	v_lshl_add_u64 v[82:83], v[42:43], 0, s[10:11]
	v_lshl_add_u64 v[84:85], v[40:41], 0, s[10:11]
	global_load_dword v101, v[70:71], off nt
	global_load_dword v102, v[72:73], off nt
	global_load_dword v103, v[74:75], off nt
	global_load_dword v104, v[76:77], off nt
	global_load_dword v105, v[78:79], off nt
	global_load_dword v106, v[80:81], off nt
	global_load_dword v107, v[82:83], off nt
	global_load_dword v108, v[84:85], off nt
	s_add_u32 s10, s10, 0x20000
	s_addc_u32 s11, s11, 0
	v_lshl_add_u64 v[70:71], v[54:55], 0, s[10:11]
	v_lshl_add_u64 v[72:73], v[52:53], 0, s[10:11]
	v_lshl_add_u64 v[74:75], v[50:51], 0, s[10:11]
	v_lshl_add_u64 v[76:77], v[48:49], 0, s[10:11]
	v_lshl_add_u64 v[78:79], v[46:47], 0, s[10:11]
	v_lshl_add_u64 v[80:81], v[44:45], 0, s[10:11]
	v_lshl_add_u64 v[82:83], v[42:43], 0, s[10:11]
	v_lshl_add_u64 v[84:85], v[40:41], 0, s[10:11]
	global_load_dword v109, v[70:71], off nt
	global_load_dword v110, v[72:73], off nt
	global_load_dword v111, v[74:75], off nt
	global_load_dword v112, v[76:77], off nt
	global_load_dword v113, v[78:79], off nt
	global_load_dword v114, v[80:81], off nt
	global_load_dword v115, v[82:83], off nt
	global_load_dword v116, v[84:85], off nt
	s_add_u32 s10, s10, 0x20000
	s_addc_u32 s11, s11, 0
	v_lshl_add_u64 v[70:71], v[54:55], 0, s[10:11]
	v_lshl_add_u64 v[72:73], v[52:53], 0, s[10:11]
	v_lshl_add_u64 v[74:75], v[50:51], 0, s[10:11]
	v_lshl_add_u64 v[76:77], v[48:49], 0, s[10:11]
	v_lshl_add_u64 v[78:79], v[46:47], 0, s[10:11]
	v_lshl_add_u64 v[80:81], v[44:45], 0, s[10:11]
	v_lshl_add_u64 v[82:83], v[42:43], 0, s[10:11]
	v_lshl_add_u64 v[84:85], v[40:41], 0, s[10:11]
	global_load_dword v117, v[70:71], off nt
	global_load_dword v118, v[72:73], off nt
	global_load_dword v119, v[74:75], off nt
	global_load_dword v120, v[76:77], off nt
	global_load_dword v121, v[78:79], off nt
	global_load_dword v122, v[80:81], off nt
	global_load_dword v123, v[82:83], off nt
	global_load_dword v124, v[84:85], off nt
	s_add_u32 s10, s10, 0x20000
	s_addc_u32 s11, s11, 0
	v_add_u32_e32 v125, 0x400, v68
	s_waitcnt vmcnt(30)
	ds_write2_b32 v68, v93, v94 offset1:66
	s_waitcnt vmcnt(28)
	ds_write2_b32 v68, v95, v96 offset0:132 offset1:198
	s_waitcnt vmcnt(26)
	ds_write2_b32 v125, v97, v98 offset0:8 offset1:74
	s_waitcnt vmcnt(24)
	ds_write2_b32 v125, v99, v100 offset0:140 offset1:206
	v_add_u32_e32 v68, 0x840, v68
	v_add_u32_e32 v125, 0x400, v68
	s_waitcnt vmcnt(22)
	ds_write2_b32 v68, v101, v102 offset1:66
	s_waitcnt vmcnt(20)
	ds_write2_b32 v68, v103, v104 offset0:132 offset1:198
	s_waitcnt vmcnt(18)
	ds_write2_b32 v125, v105, v106 offset0:8 offset1:74
	s_waitcnt vmcnt(16)
	ds_write2_b32 v125, v107, v108 offset0:140 offset1:206
	v_add_u32_e32 v68, 0x840, v68
	v_add_u32_e32 v125, 0x400, v68
	s_waitcnt vmcnt(14)
	ds_write2_b32 v68, v109, v110 offset1:66
	s_waitcnt vmcnt(12)
	ds_write2_b32 v68, v111, v112 offset0:132 offset1:198
	s_waitcnt vmcnt(10)
	ds_write2_b32 v125, v113, v114 offset0:8 offset1:74
	s_waitcnt vmcnt(8)
	ds_write2_b32 v125, v115, v116 offset0:140 offset1:206
	v_add_u32_e32 v68, 0x840, v68
	v_add_u32_e32 v125, 0x400, v68
	s_waitcnt vmcnt(6)
	ds_write2_b32 v68, v117, v118 offset1:66
	s_waitcnt vmcnt(4)
	ds_write2_b32 v68, v119, v120 offset0:132 offset1:198
	s_waitcnt vmcnt(2)
	ds_write2_b32 v125, v121, v122 offset0:8 offset1:74
	s_waitcnt vmcnt(0)
	ds_write2_b32 v125, v123, v124 offset0:140 offset1:206
	v_add_u32_e32 v68, 0x840, v68
	s_add_i32 s0, s27, 0xffff83e0
	s_waitcnt lgkmcnt(0)
	s_and_b32 s10, s0, 0xffc0
	s_lshl_b32 s0, s0, 5
	ds_read2_b32 v[44:45], v56 offset0:33 offset1:41
	ds_read2_b32 v[46:47], v56 offset1:8
	ds_read2_b32 v[48:49], v56 offset0:66 offset1:74
	ds_read2_b32 v[50:51], v56 offset0:99 offset1:107
	ds_read2_b32 v[52:53], v56 offset0:132 offset1:140
	ds_read2_b32 v[54:55], v56 offset0:165 offset1:173
	ds_read2_b32 v[68:69], v56 offset0:198 offset1:206
	ds_read2_b32 v[70:71], v56 offset0:231 offset1:239
	s_and_b32 s11, s0, 0x7e0
	v_add_u32_e32 v74, s11, v1
	s_lshl_b32 s0, s10, 1
	v_ashrrev_i32_e32 v75, 31, v74
	v_lshl_add_u64 v[72:73], v[6:7], 0, s[0:1]
	v_lshlrev_b64 v[74:75], 12, v[74:75]
	s_waitcnt lgkmcnt(6)
	v_cvt_pk_bf16_f32 v40, v46, v44
	s_waitcnt lgkmcnt(4)
	v_cvt_pk_bf16_f32 v41, v48, v50
	s_waitcnt lgkmcnt(2)
	v_cvt_pk_bf16_f32 v42, v52, v54
	s_waitcnt lgkmcnt(0)
	v_cvt_pk_bf16_f32 v43, v68, v70
	v_lshl_add_u64 v[74:75], v[72:73], 0, v[74:75]
	v_add_u32_e32 v44, s11, v57
	global_store_dwordx4 v[74:75], v[40:43], off
	s_nop 1
	v_cvt_pk_bf16_f32 v40, v47, v45
	v_ashrrev_i32_e32 v45, 31, v44
	v_cvt_pk_bf16_f32 v41, v49, v51
	v_cvt_pk_bf16_f32 v42, v53, v55
	v_cvt_pk_bf16_f32 v43, v69, v71
	v_lshlrev_b64 v[44:45], 12, v[44:45]
	ds_read2_b32 v[46:47], v56 offset0:49 offset1:57
	ds_read2_b32 v[48:49], v56 offset0:16 offset1:24
	ds_read2_b32 v[50:51], v56 offset0:82 offset1:90
	ds_read2_b32 v[52:53], v56 offset0:115 offset1:123
	ds_read2_b32 v[54:55], v56 offset0:148 offset1:156
	ds_read2_b32 v[68:69], v56 offset0:181 offset1:189
	ds_read2_b32 v[70:71], v56 offset0:214 offset1:222
	ds_read2_b32 v[74:75], v56 offset0:247 offset1:255
	v_lshl_add_u64 v[44:45], v[72:73], 0, v[44:45]
	global_store_dwordx4 v[44:45], v[40:43], off
	v_add_u32_e32 v44, s11, v58
	v_ashrrev_i32_e32 v45, 31, v44
	v_lshlrev_b64 v[44:45], 12, v[44:45]
	s_waitcnt lgkmcnt(6)
	v_cvt_pk_bf16_f32 v40, v48, v46
	s_waitcnt lgkmcnt(4)
	v_cvt_pk_bf16_f32 v41, v50, v52
	s_waitcnt lgkmcnt(2)
	v_cvt_pk_bf16_f32 v42, v54, v68
	s_waitcnt lgkmcnt(0)
	v_cvt_pk_bf16_f32 v43, v70, v74
	v_lshl_add_u64 v[44:45], v[72:73], 0, v[44:45]
	global_store_dwordx4 v[44:45], v[40:43], off
	v_add_u32_e32 v44, s11, v59
	v_ashrrev_i32_e32 v45, 31, v44
	v_lshlrev_b64 v[44:45], 12, v[44:45]
	v_cvt_pk_bf16_f32 v40, v49, v47
	v_cvt_pk_bf16_f32 v41, v51, v53
	v_cvt_pk_bf16_f32 v42, v55, v69
	v_cvt_pk_bf16_f32 v43, v71, v75
	v_lshl_add_u64 v[44:45], v[72:73], 0, v[44:45]
	global_store_dwordx4 v[44:45], v[40:43], off
	s_waitcnt lgkmcnt(0)
	s_mov_b64 s[10:11], 0

.LBB0_35:
	v_lshl_add_u64 v[70:71], v[54:55], 0, s[10:11]
	v_lshl_add_u64 v[72:73], v[52:53], 0, s[10:11]
	v_lshl_add_u64 v[74:75], v[50:51], 0, s[10:11]
	v_lshl_add_u64 v[76:77], v[48:49], 0, s[10:11]
	v_lshl_add_u64 v[78:79], v[46:47], 0, s[10:11]
	v_lshl_add_u64 v[80:81], v[44:45], 0, s[10:11]
	v_lshl_add_u64 v[82:83], v[42:43], 0, s[10:11]
	v_lshl_add_u64 v[84:85], v[40:41], 0, s[10:11]
	global_load_dword v93, v[70:71], off nt
	global_load_dword v94, v[72:73], off nt
	global_load_dword v95, v[74:75], off nt
	global_load_dword v96, v[76:77], off nt
	global_load_dword v97, v[78:79], off nt
	global_load_dword v98, v[80:81], off nt
	global_load_dword v99, v[82:83], off nt
	global_load_dword v100, v[84:85], off nt
	s_add_u32 s10, s10, 0x20000
	s_addc_u32 s11, s11, 0
	v_lshl_add_u64 v[70:71], v[54:55], 0, s[10:11]
	v_lshl_add_u64 v[72:73], v[52:53], 0, s[10:11]
	v_lshl_add_u64 v[74:75], v[50:51], 0, s[10:11]
	v_lshl_add_u64 v[76:77], v[48:49], 0, s[10:11]
	v_lshl_add_u64 v[78:79], v[46:47], 0, s[10:11]
	v_lshl_add_u64 v[80:81], v[44:45], 0, s[10:11]
	v_lshl_add_u64 v[82:83], v[42:43], 0, s[10:11]
	v_lshl_add_u64 v[84:85], v[40:41], 0, s[10:11]
	global_load_dword v101, v[70:71], off nt
	global_load_dword v102, v[72:73], off nt
	global_load_dword v103, v[74:75], off nt
	global_load_dword v104, v[76:77], off nt
	global_load_dword v105, v[78:79], off nt
	global_load_dword v106, v[80:81], off nt
	global_load_dword v107, v[82:83], off nt
	global_load_dword v108, v[84:85], off nt
	s_add_u32 s10, s10, 0x20000
	s_addc_u32 s11, s11, 0
	v_lshl_add_u64 v[70:71], v[54:55], 0, s[10:11]
	v_lshl_add_u64 v[72:73], v[52:53], 0, s[10:11]
	v_lshl_add_u64 v[74:75], v[50:51], 0, s[10:11]
	v_lshl_add_u64 v[76:77], v[48:49], 0, s[10:11]
	v_lshl_add_u64 v[78:79], v[46:47], 0, s[10:11]
	v_lshl_add_u64 v[80:81], v[44:45], 0, s[10:11]
	v_lshl_add_u64 v[82:83], v[42:43], 0, s[10:11]
	v_lshl_add_u64 v[84:85], v[40:41], 0, s[10:11]
	global_load_dword v109, v[70:71], off nt
	global_load_dword v110, v[72:73], off nt
	global_load_dword v111, v[74:75], off nt
	global_load_dword v112, v[76:77], off nt
	global_load_dword v113, v[78:79], off nt
	global_load_dword v114, v[80:81], off nt
	global_load_dword v115, v[82:83], off nt
	global_load_dword v116, v[84:85], off nt
	s_add_u32 s10, s10, 0x20000
	s_addc_u32 s11, s11, 0
	v_lshl_add_u64 v[70:71], v[54:55], 0, s[10:11]
	v_lshl_add_u64 v[72:73], v[52:53], 0, s[10:11]
	v_lshl_add_u64 v[74:75], v[50:51], 0, s[10:11]
	v_lshl_add_u64 v[76:77], v[48:49], 0, s[10:11]
	v_lshl_add_u64 v[78:79], v[46:47], 0, s[10:11]
	v_lshl_add_u64 v[80:81], v[44:45], 0, s[10:11]
	v_lshl_add_u64 v[82:83], v[42:43], 0, s[10:11]
	v_lshl_add_u64 v[84:85], v[40:41], 0, s[10:11]
	global_load_dword v117, v[70:71], off nt
	global_load_dword v118, v[72:73], off nt
	global_load_dword v119, v[74:75], off nt
	global_load_dword v120, v[76:77], off nt
	global_load_dword v121, v[78:79], off nt
	global_load_dword v122, v[80:81], off nt
	global_load_dword v123, v[82:83], off nt
	global_load_dword v124, v[84:85], off nt
	s_add_u32 s10, s10, 0x20000
	s_addc_u32 s11, s11, 0
	v_add_u32_e32 v125, 0x400, v68
	s_waitcnt vmcnt(30)
	ds_write2_b32 v68, v93, v94 offset1:66
	s_waitcnt vmcnt(28)
	ds_write2_b32 v68, v95, v96 offset0:132 offset1:198
	s_waitcnt vmcnt(26)
	ds_write2_b32 v125, v97, v98 offset0:8 offset1:74
	s_waitcnt vmcnt(24)
	ds_write2_b32 v125, v99, v100 offset0:140 offset1:206
	v_add_u32_e32 v68, 0x840, v68
	v_add_u32_e32 v125, 0x400, v68
	s_waitcnt vmcnt(22)
	ds_write2_b32 v68, v101, v102 offset1:66
	s_waitcnt vmcnt(20)
	ds_write2_b32 v68, v103, v104 offset0:132 offset1:198
	s_waitcnt vmcnt(18)
	ds_write2_b32 v125, v105, v106 offset0:8 offset1:74
	s_waitcnt vmcnt(16)
	ds_write2_b32 v125, v107, v108 offset0:140 offset1:206
	v_add_u32_e32 v68, 0x840, v68
	v_add_u32_e32 v125, 0x400, v68
	s_waitcnt vmcnt(14)
	ds_write2_b32 v68, v109, v110 offset1:66
	s_waitcnt vmcnt(12)
	ds_write2_b32 v68, v111, v112 offset0:132 offset1:198
	s_waitcnt vmcnt(10)
	ds_write2_b32 v125, v113, v114 offset0:8 offset1:74
	s_waitcnt vmcnt(8)
	ds_write2_b32 v125, v115, v116 offset0:140 offset1:206
	v_add_u32_e32 v68, 0x840, v68
	v_add_u32_e32 v125, 0x400, v68
	s_waitcnt vmcnt(6)
	ds_write2_b32 v68, v117, v118 offset1:66
	s_waitcnt vmcnt(4)
	ds_write2_b32 v68, v119, v120 offset0:132 offset1:198
	s_waitcnt vmcnt(2)
	ds_write2_b32 v125, v121, v122 offset0:8 offset1:74
	s_waitcnt vmcnt(0)
	ds_write2_b32 v125, v123, v124 offset0:140 offset1:206
	v_add_u32_e32 v68, 0x840, v68
	s_add_i32 s0, s27, 0xffff8be0
	s_waitcnt lgkmcnt(0)
	s_and_b32 s10, s0, 0xffc0
	s_lshl_b32 s0, s0, 5
	ds_read2_b32 v[44:45], v56 offset0:33 offset1:41
	ds_read2_b32 v[46:47], v56 offset1:8
	ds_read2_b32 v[48:49], v56 offset0:66 offset1:74
	ds_read2_b32 v[50:51], v56 offset0:99 offset1:107
	ds_read2_b32 v[52:53], v56 offset0:132 offset1:140
	ds_read2_b32 v[54:55], v56 offset0:165 offset1:173
	ds_read2_b32 v[68:69], v56 offset0:198 offset1:206
	ds_read2_b32 v[70:71], v56 offset0:231 offset1:239
	s_and_b32 s11, s0, 0x7e0
	v_add_u32_e32 v74, s11, v1
	s_lshl_b32 s0, s10, 1
	v_ashrrev_i32_e32 v75, 31, v74
	v_lshl_add_u64 v[72:73], v[8:9], 0, s[0:1]
	v_lshlrev_b64 v[74:75], 12, v[74:75]
	s_waitcnt lgkmcnt(6)
	v_cvt_pk_bf16_f32 v40, v46, v44
	s_waitcnt lgkmcnt(4)
	v_cvt_pk_bf16_f32 v41, v48, v50
	s_waitcnt lgkmcnt(2)
	v_cvt_pk_bf16_f32 v42, v52, v54
	s_waitcnt lgkmcnt(0)
	v_cvt_pk_bf16_f32 v43, v68, v70
	v_lshl_add_u64 v[74:75], v[72:73], 0, v[74:75]
	v_add_u32_e32 v44, s11, v57
	global_store_dwordx4 v[74:75], v[40:43], off
	s_nop 1
	v_cvt_pk_bf16_f32 v40, v47, v45
	v_ashrrev_i32_e32 v45, 31, v44
	v_cvt_pk_bf16_f32 v41, v49, v51
	v_cvt_pk_bf16_f32 v42, v53, v55
	v_cvt_pk_bf16_f32 v43, v69, v71
	v_lshlrev_b64 v[44:45], 12, v[44:45]
	ds_read2_b32 v[46:47], v56 offset0:49 offset1:57
	ds_read2_b32 v[48:49], v56 offset0:16 offset1:24
	ds_read2_b32 v[50:51], v56 offset0:82 offset1:90
	ds_read2_b32 v[52:53], v56 offset0:115 offset1:123
	ds_read2_b32 v[54:55], v56 offset0:148 offset1:156
	ds_read2_b32 v[68:69], v56 offset0:181 offset1:189
	ds_read2_b32 v[70:71], v56 offset0:214 offset1:222
	ds_read2_b32 v[74:75], v56 offset0:247 offset1:255
	v_lshl_add_u64 v[44:45], v[72:73], 0, v[44:45]
	global_store_dwordx4 v[44:45], v[40:43], off
	v_add_u32_e32 v44, s11, v58
	v_ashrrev_i32_e32 v45, 31, v44
	v_lshlrev_b64 v[44:45], 12, v[44:45]
	s_waitcnt lgkmcnt(6)
	v_cvt_pk_bf16_f32 v40, v48, v46
	s_waitcnt lgkmcnt(4)
	v_cvt_pk_bf16_f32 v41, v50, v52
	s_waitcnt lgkmcnt(2)
	v_cvt_pk_bf16_f32 v42, v54, v68
	s_waitcnt lgkmcnt(0)
	v_cvt_pk_bf16_f32 v43, v70, v74
	v_lshl_add_u64 v[44:45], v[72:73], 0, v[44:45]
	global_store_dwordx4 v[44:45], v[40:43], off
	v_add_u32_e32 v44, s11, v59
	v_ashrrev_i32_e32 v45, 31, v44
	v_lshlrev_b64 v[44:45], 12, v[44:45]
	v_cvt_pk_bf16_f32 v40, v49, v47
	v_cvt_pk_bf16_f32 v41, v51, v53
	v_cvt_pk_bf16_f32 v42, v55, v69
	v_cvt_pk_bf16_f32 v43, v71, v75
	v_lshl_add_u64 v[44:45], v[72:73], 0, v[44:45]
	global_store_dwordx4 v[44:45], v[40:43], off
	s_waitcnt lgkmcnt(0)

.LBB0_40:
	v_lshl_add_u64 v[70:71], v[54:55], 0, s[10:11]
	v_lshl_add_u64 v[72:73], v[52:53], 0, s[10:11]
	v_lshl_add_u64 v[74:75], v[50:51], 0, s[10:11]
	v_lshl_add_u64 v[76:77], v[48:49], 0, s[10:11]
	v_lshl_add_u64 v[78:79], v[46:47], 0, s[10:11]
	v_lshl_add_u64 v[80:81], v[44:45], 0, s[10:11]
	v_lshl_add_u64 v[82:83], v[42:43], 0, s[10:11]
	v_lshl_add_u64 v[84:85], v[40:41], 0, s[10:11]
	global_load_dword v93, v[70:71], off nt
	global_load_dword v94, v[72:73], off nt
	global_load_dword v95, v[74:75], off nt
	global_load_dword v96, v[76:77], off nt
	global_load_dword v97, v[78:79], off nt
	global_load_dword v98, v[80:81], off nt
	global_load_dword v99, v[82:83], off nt
	global_load_dword v100, v[84:85], off nt
	s_add_u32 s10, s10, 0x20000
	s_addc_u32 s11, s11, 0
	v_lshl_add_u64 v[70:71], v[54:55], 0, s[10:11]
	v_lshl_add_u64 v[72:73], v[52:53], 0, s[10:11]
	v_lshl_add_u64 v[74:75], v[50:51], 0, s[10:11]
	v_lshl_add_u64 v[76:77], v[48:49], 0, s[10:11]
	v_lshl_add_u64 v[78:79], v[46:47], 0, s[10:11]
	v_lshl_add_u64 v[80:81], v[44:45], 0, s[10:11]
	v_lshl_add_u64 v[82:83], v[42:43], 0, s[10:11]
	v_lshl_add_u64 v[84:85], v[40:41], 0, s[10:11]
	global_load_dword v101, v[70:71], off nt
	global_load_dword v102, v[72:73], off nt
	global_load_dword v103, v[74:75], off nt
	global_load_dword v104, v[76:77], off nt
	global_load_dword v105, v[78:79], off nt
	global_load_dword v106, v[80:81], off nt
	global_load_dword v107, v[82:83], off nt
	global_load_dword v108, v[84:85], off nt
	s_add_u32 s10, s10, 0x20000
	s_addc_u32 s11, s11, 0
	v_lshl_add_u64 v[70:71], v[54:55], 0, s[10:11]
	v_lshl_add_u64 v[72:73], v[52:53], 0, s[10:11]
	v_lshl_add_u64 v[74:75], v[50:51], 0, s[10:11]
	v_lshl_add_u64 v[76:77], v[48:49], 0, s[10:11]
	v_lshl_add_u64 v[78:79], v[46:47], 0, s[10:11]
	v_lshl_add_u64 v[80:81], v[44:45], 0, s[10:11]
	v_lshl_add_u64 v[82:83], v[42:43], 0, s[10:11]
	v_lshl_add_u64 v[84:85], v[40:41], 0, s[10:11]
	global_load_dword v109, v[70:71], off nt
	global_load_dword v110, v[72:73], off nt
	global_load_dword v111, v[74:75], off nt
	global_load_dword v112, v[76:77], off nt
	global_load_dword v113, v[78:79], off nt
	global_load_dword v114, v[80:81], off nt
	global_load_dword v115, v[82:83], off nt
	global_load_dword v116, v[84:85], off nt
	s_add_u32 s10, s10, 0x20000
	s_addc_u32 s11, s11, 0
	v_lshl_add_u64 v[70:71], v[54:55], 0, s[10:11]
	v_lshl_add_u64 v[72:73], v[52:53], 0, s[10:11]
	v_lshl_add_u64 v[74:75], v[50:51], 0, s[10:11]
	v_lshl_add_u64 v[76:77], v[48:49], 0, s[10:11]
	v_lshl_add_u64 v[78:79], v[46:47], 0, s[10:11]
	v_lshl_add_u64 v[80:81], v[44:45], 0, s[10:11]
	v_lshl_add_u64 v[82:83], v[42:43], 0, s[10:11]
	v_lshl_add_u64 v[84:85], v[40:41], 0, s[10:11]
	global_load_dword v117, v[70:71], off nt
	global_load_dword v118, v[72:73], off nt
	global_load_dword v119, v[74:75], off nt
	global_load_dword v120, v[76:77], off nt
	global_load_dword v121, v[78:79], off nt
	global_load_dword v122, v[80:81], off nt
	global_load_dword v123, v[82:83], off nt
	global_load_dword v124, v[84:85], off nt
	s_add_u32 s10, s10, 0x20000
	s_addc_u32 s11, s11, 0
	v_add_u32_e32 v125, 0x400, v68
	s_waitcnt vmcnt(30)
	ds_write2_b32 v68, v93, v94 offset1:66
	s_waitcnt vmcnt(28)
	ds_write2_b32 v68, v95, v96 offset0:132 offset1:198
	s_waitcnt vmcnt(26)
	ds_write2_b32 v125, v97, v98 offset0:8 offset1:74
	s_waitcnt vmcnt(24)
	ds_write2_b32 v125, v99, v100 offset0:140 offset1:206
	v_add_u32_e32 v68, 0x840, v68
	v_add_u32_e32 v125, 0x400, v68
	s_waitcnt vmcnt(22)
	ds_write2_b32 v68, v101, v102 offset1:66
	s_waitcnt vmcnt(20)
	ds_write2_b32 v68, v103, v104 offset0:132 offset1:198
	s_waitcnt vmcnt(18)
	ds_write2_b32 v125, v105, v106 offset0:8 offset1:74
	s_waitcnt vmcnt(16)
	ds_write2_b32 v125, v107, v108 offset0:140 offset1:206
	v_add_u32_e32 v68, 0x840, v68
	v_add_u32_e32 v125, 0x400, v68
	s_waitcnt vmcnt(14)
	ds_write2_b32 v68, v109, v110 offset1:66
	s_waitcnt vmcnt(12)
	ds_write2_b32 v68, v111, v112 offset0:132 offset1:198
	s_waitcnt vmcnt(10)
	ds_write2_b32 v125, v113, v114 offset0:8 offset1:74
	s_waitcnt vmcnt(8)
	ds_write2_b32 v125, v115, v116 offset0:140 offset1:206
	v_add_u32_e32 v68, 0x840, v68
	v_add_u32_e32 v125, 0x400, v68
	s_waitcnt vmcnt(6)
	ds_write2_b32 v68, v117, v118 offset1:66
	s_waitcnt vmcnt(4)
	ds_write2_b32 v68, v119, v120 offset0:132 offset1:198
	s_waitcnt vmcnt(2)
	ds_write2_b32 v125, v121, v122 offset0:8 offset1:74
	s_waitcnt vmcnt(0)
	ds_write2_b32 v125, v123, v124 offset0:140 offset1:206
	v_add_u32_e32 v68, 0x840, v68
	s_add_i32 s0, s27, 0xffff93e0
	s_waitcnt lgkmcnt(0)
	s_and_b32 s10, s0, 0xffc0
	s_lshl_b32 s0, s0, 5
	ds_read2_b32 v[44:45], v56 offset0:33 offset1:41
	ds_read2_b32 v[46:47], v56 offset1:8
	ds_read2_b32 v[48:49], v56 offset0:66 offset1:74
	ds_read2_b32 v[50:51], v56 offset0:99 offset1:107
	ds_read2_b32 v[52:53], v56 offset0:132 offset1:140
	ds_read2_b32 v[54:55], v56 offset0:165 offset1:173
	ds_read2_b32 v[68:69], v56 offset0:198 offset1:206
	ds_read2_b32 v[70:71], v56 offset0:231 offset1:239
	s_and_b32 s11, s0, 0x7e0
	v_add_u32_e32 v74, s11, v1
	s_lshl_b32 s0, s10, 1
	v_ashrrev_i32_e32 v75, 31, v74
	v_lshl_add_u64 v[72:73], v[10:11], 0, s[0:1]
	v_lshlrev_b64 v[74:75], 12, v[74:75]
	s_waitcnt lgkmcnt(6)
	v_cvt_pk_bf16_f32 v40, v46, v44
	s_waitcnt lgkmcnt(4)
	v_cvt_pk_bf16_f32 v41, v48, v50
	s_waitcnt lgkmcnt(2)
	v_cvt_pk_bf16_f32 v42, v52, v54
	s_waitcnt lgkmcnt(0)
	v_cvt_pk_bf16_f32 v43, v68, v70
	v_lshl_add_u64 v[74:75], v[72:73], 0, v[74:75]
	v_add_u32_e32 v44, s11, v57
	global_store_dwordx4 v[74:75], v[40:43], off
	s_nop 1
	v_cvt_pk_bf16_f32 v40, v47, v45
	v_ashrrev_i32_e32 v45, 31, v44
	v_cvt_pk_bf16_f32 v41, v49, v51
	v_cvt_pk_bf16_f32 v42, v53, v55
	v_cvt_pk_bf16_f32 v43, v69, v71
	v_lshlrev_b64 v[44:45], 12, v[44:45]
	ds_read2_b32 v[46:47], v56 offset0:49 offset1:57
	ds_read2_b32 v[48:49], v56 offset0:16 offset1:24
	ds_read2_b32 v[50:51], v56 offset0:82 offset1:90
	ds_read2_b32 v[52:53], v56 offset0:115 offset1:123
	ds_read2_b32 v[54:55], v56 offset0:148 offset1:156
	ds_read2_b32 v[68:69], v56 offset0:181 offset1:189
	ds_read2_b32 v[70:71], v56 offset0:214 offset1:222
	ds_read2_b32 v[74:75], v56 offset0:247 offset1:255
	v_lshl_add_u64 v[44:45], v[72:73], 0, v[44:45]
	global_store_dwordx4 v[44:45], v[40:43], off
	v_add_u32_e32 v44, s11, v58
	v_ashrrev_i32_e32 v45, 31, v44
	v_lshlrev_b64 v[44:45], 12, v[44:45]
	s_waitcnt lgkmcnt(6)
	v_cvt_pk_bf16_f32 v40, v48, v46
	s_waitcnt lgkmcnt(4)
	v_cvt_pk_bf16_f32 v41, v50, v52
	s_waitcnt lgkmcnt(2)
	v_cvt_pk_bf16_f32 v42, v54, v68
	s_waitcnt lgkmcnt(0)
	v_cvt_pk_bf16_f32 v43, v70, v74
	v_lshl_add_u64 v[44:45], v[72:73], 0, v[44:45]
	global_store_dwordx4 v[44:45], v[40:43], off
	v_add_u32_e32 v44, s11, v59
	v_ashrrev_i32_e32 v45, 31, v44
	v_lshlrev_b64 v[44:45], 12, v[44:45]
	v_cvt_pk_bf16_f32 v40, v49, v47
	v_cvt_pk_bf16_f32 v41, v51, v53
	v_cvt_pk_bf16_f32 v42, v55, v69
	v_cvt_pk_bf16_f32 v43, v71, v75
	v_lshl_add_u64 v[44:45], v[72:73], 0, v[44:45]
	global_store_dwordx4 v[44:45], v[40:43], off
	s_waitcnt lgkmcnt(0)

.LBB0_45:
	v_lshl_add_u64 v[70:71], v[54:55], 0, s[10:11]
	v_lshl_add_u64 v[72:73], v[52:53], 0, s[10:11]
	v_lshl_add_u64 v[74:75], v[50:51], 0, s[10:11]
	v_lshl_add_u64 v[76:77], v[48:49], 0, s[10:11]
	v_lshl_add_u64 v[78:79], v[46:47], 0, s[10:11]
	v_lshl_add_u64 v[80:81], v[44:45], 0, s[10:11]
	v_lshl_add_u64 v[82:83], v[42:43], 0, s[10:11]
	v_lshl_add_u64 v[84:85], v[40:41], 0, s[10:11]
	global_load_dword v93, v[70:71], off nt
	global_load_dword v94, v[72:73], off nt
	global_load_dword v95, v[74:75], off nt
	global_load_dword v96, v[76:77], off nt
	global_load_dword v97, v[78:79], off nt
	global_load_dword v98, v[80:81], off nt
	global_load_dword v99, v[82:83], off nt
	global_load_dword v100, v[84:85], off nt
	s_add_u32 s10, s10, 0x20000
	s_addc_u32 s11, s11, 0
	v_lshl_add_u64 v[70:71], v[54:55], 0, s[10:11]
	v_lshl_add_u64 v[72:73], v[52:53], 0, s[10:11]
	v_lshl_add_u64 v[74:75], v[50:51], 0, s[10:11]
	v_lshl_add_u64 v[76:77], v[48:49], 0, s[10:11]
	v_lshl_add_u64 v[78:79], v[46:47], 0, s[10:11]
	v_lshl_add_u64 v[80:81], v[44:45], 0, s[10:11]
	v_lshl_add_u64 v[82:83], v[42:43], 0, s[10:11]
	v_lshl_add_u64 v[84:85], v[40:41], 0, s[10:11]
	global_load_dword v101, v[70:71], off nt
	global_load_dword v102, v[72:73], off nt
	global_load_dword v103, v[74:75], off nt
	global_load_dword v104, v[76:77], off nt
	global_load_dword v105, v[78:79], off nt
	global_load_dword v106, v[80:81], off nt
	global_load_dword v107, v[82:83], off nt
	global_load_dword v108, v[84:85], off nt
	s_add_u32 s10, s10, 0x20000
	s_addc_u32 s11, s11, 0
	v_lshl_add_u64 v[70:71], v[54:55], 0, s[10:11]
	v_lshl_add_u64 v[72:73], v[52:53], 0, s[10:11]
	v_lshl_add_u64 v[74:75], v[50:51], 0, s[10:11]
	v_lshl_add_u64 v[76:77], v[48:49], 0, s[10:11]
	v_lshl_add_u64 v[78:79], v[46:47], 0, s[10:11]
	v_lshl_add_u64 v[80:81], v[44:45], 0, s[10:11]
	v_lshl_add_u64 v[82:83], v[42:43], 0, s[10:11]
	v_lshl_add_u64 v[84:85], v[40:41], 0, s[10:11]
	global_load_dword v109, v[70:71], off nt
	global_load_dword v110, v[72:73], off nt
	global_load_dword v111, v[74:75], off nt
	global_load_dword v112, v[76:77], off nt
	global_load_dword v113, v[78:79], off nt
	global_load_dword v114, v[80:81], off nt
	global_load_dword v115, v[82:83], off nt
	global_load_dword v116, v[84:85], off nt
	s_add_u32 s10, s10, 0x20000
	s_addc_u32 s11, s11, 0
	v_lshl_add_u64 v[70:71], v[54:55], 0, s[10:11]
	v_lshl_add_u64 v[72:73], v[52:53], 0, s[10:11]
	v_lshl_add_u64 v[74:75], v[50:51], 0, s[10:11]
	v_lshl_add_u64 v[76:77], v[48:49], 0, s[10:11]
	v_lshl_add_u64 v[78:79], v[46:47], 0, s[10:11]
	v_lshl_add_u64 v[80:81], v[44:45], 0, s[10:11]
	v_lshl_add_u64 v[82:83], v[42:43], 0, s[10:11]
	v_lshl_add_u64 v[84:85], v[40:41], 0, s[10:11]
	global_load_dword v117, v[70:71], off nt
	global_load_dword v118, v[72:73], off nt
	global_load_dword v119, v[74:75], off nt
	global_load_dword v120, v[76:77], off nt
	global_load_dword v121, v[78:79], off nt
	global_load_dword v122, v[80:81], off nt
	global_load_dword v123, v[82:83], off nt
	global_load_dword v124, v[84:85], off nt
	s_add_u32 s10, s10, 0x20000
	s_addc_u32 s11, s11, 0
	v_add_u32_e32 v125, 0x400, v68
	s_waitcnt vmcnt(30)
	ds_write2_b32 v68, v93, v94 offset1:66
	s_waitcnt vmcnt(28)
	ds_write2_b32 v68, v95, v96 offset0:132 offset1:198
	s_waitcnt vmcnt(26)
	ds_write2_b32 v125, v97, v98 offset0:8 offset1:74
	s_waitcnt vmcnt(24)
	ds_write2_b32 v125, v99, v100 offset0:140 offset1:206
	v_add_u32_e32 v68, 0x840, v68
	v_add_u32_e32 v125, 0x400, v68
	s_waitcnt vmcnt(22)
	ds_write2_b32 v68, v101, v102 offset1:66
	s_waitcnt vmcnt(20)
	ds_write2_b32 v68, v103, v104 offset0:132 offset1:198
	s_waitcnt vmcnt(18)
	ds_write2_b32 v125, v105, v106 offset0:8 offset1:74
	s_waitcnt vmcnt(16)
	ds_write2_b32 v125, v107, v108 offset0:140 offset1:206
	v_add_u32_e32 v68, 0x840, v68
	v_add_u32_e32 v125, 0x400, v68
	s_waitcnt vmcnt(14)
	ds_write2_b32 v68, v109, v110 offset1:66
	s_waitcnt vmcnt(12)
	ds_write2_b32 v68, v111, v112 offset0:132 offset1:198
	s_waitcnt vmcnt(10)
	ds_write2_b32 v125, v113, v114 offset0:8 offset1:74
	s_waitcnt vmcnt(8)
	ds_write2_b32 v125, v115, v116 offset0:140 offset1:206
	v_add_u32_e32 v68, 0x840, v68
	v_add_u32_e32 v125, 0x400, v68
	s_waitcnt vmcnt(6)
	ds_write2_b32 v68, v117, v118 offset1:66
	s_waitcnt vmcnt(4)
	ds_write2_b32 v68, v119, v120 offset0:132 offset1:198
	s_waitcnt vmcnt(2)
	ds_write2_b32 v125, v121, v122 offset0:8 offset1:74
	s_waitcnt vmcnt(0)
	ds_write2_b32 v125, v123, v124 offset0:140 offset1:206
	v_add_u32_e32 v68, 0x840, v68
	s_add_i32 s0, s27, 0xffff9be0
	s_waitcnt lgkmcnt(0)
	s_and_b32 s10, s0, 0xffc0
	s_lshl_b32 s0, s0, 5
	ds_read2_b32 v[44:45], v56 offset0:33 offset1:41
	ds_read2_b32 v[46:47], v56 offset1:8
	ds_read2_b32 v[48:49], v56 offset0:66 offset1:74
	ds_read2_b32 v[50:51], v56 offset0:99 offset1:107
	ds_read2_b32 v[52:53], v56 offset0:132 offset1:140
	ds_read2_b32 v[54:55], v56 offset0:165 offset1:173
	ds_read2_b32 v[68:69], v56 offset0:198 offset1:206
	ds_read2_b32 v[70:71], v56 offset0:231 offset1:239
	s_and_b32 s11, s0, 0x7e0
	v_add_u32_e32 v74, s11, v1
	s_lshl_b32 s0, s10, 1
	v_ashrrev_i32_e32 v75, 31, v74
	v_lshl_add_u64 v[72:73], v[12:13], 0, s[0:1]
	v_lshlrev_b64 v[74:75], 12, v[74:75]
	s_waitcnt lgkmcnt(6)
	v_cvt_pk_bf16_f32 v40, v46, v44
	s_waitcnt lgkmcnt(4)
	v_cvt_pk_bf16_f32 v41, v48, v50
	s_waitcnt lgkmcnt(2)
	v_cvt_pk_bf16_f32 v42, v52, v54
	s_waitcnt lgkmcnt(0)
	v_cvt_pk_bf16_f32 v43, v68, v70
	v_lshl_add_u64 v[74:75], v[72:73], 0, v[74:75]
	v_add_u32_e32 v44, s11, v57
	global_store_dwordx4 v[74:75], v[40:43], off
	s_nop 1
	v_cvt_pk_bf16_f32 v40, v47, v45
	v_ashrrev_i32_e32 v45, 31, v44
	v_cvt_pk_bf16_f32 v41, v49, v51
	v_cvt_pk_bf16_f32 v42, v53, v55
	v_cvt_pk_bf16_f32 v43, v69, v71
	v_lshlrev_b64 v[44:45], 12, v[44:45]
	ds_read2_b32 v[46:47], v56 offset0:49 offset1:57
	ds_read2_b32 v[48:49], v56 offset0:16 offset1:24
	ds_read2_b32 v[50:51], v56 offset0:82 offset1:90
	ds_read2_b32 v[52:53], v56 offset0:115 offset1:123
	ds_read2_b32 v[54:55], v56 offset0:148 offset1:156
	ds_read2_b32 v[68:69], v56 offset0:181 offset1:189
	ds_read2_b32 v[70:71], v56 offset0:214 offset1:222
	ds_read2_b32 v[74:75], v56 offset0:247 offset1:255
	v_lshl_add_u64 v[44:45], v[72:73], 0, v[44:45]
	global_store_dwordx4 v[44:45], v[40:43], off
	v_add_u32_e32 v44, s11, v58
	v_ashrrev_i32_e32 v45, 31, v44
	v_lshlrev_b64 v[44:45], 12, v[44:45]
	s_waitcnt lgkmcnt(6)
	v_cvt_pk_bf16_f32 v40, v48, v46
	s_waitcnt lgkmcnt(4)
	v_cvt_pk_bf16_f32 v41, v50, v52
	s_waitcnt lgkmcnt(2)
	v_cvt_pk_bf16_f32 v42, v54, v68
	s_waitcnt lgkmcnt(0)
	v_cvt_pk_bf16_f32 v43, v70, v74
	v_lshl_add_u64 v[44:45], v[72:73], 0, v[44:45]
	global_store_dwordx4 v[44:45], v[40:43], off
	v_add_u32_e32 v44, s11, v59
	v_ashrrev_i32_e32 v45, 31, v44
	v_lshlrev_b64 v[44:45], 12, v[44:45]
	v_cvt_pk_bf16_f32 v40, v49, v47
	v_cvt_pk_bf16_f32 v41, v51, v53
	v_cvt_pk_bf16_f32 v42, v55, v69
	v_cvt_pk_bf16_f32 v43, v71, v75
	v_lshl_add_u64 v[44:45], v[72:73], 0, v[44:45]
	global_store_dwordx4 v[44:45], v[40:43], off
	s_waitcnt lgkmcnt(0)

.LBB0_50:
	v_lshl_add_u64 v[70:71], v[54:55], 0, s[10:11]
	v_lshl_add_u64 v[72:73], v[52:53], 0, s[10:11]
	v_lshl_add_u64 v[74:75], v[50:51], 0, s[10:11]
	v_lshl_add_u64 v[76:77], v[48:49], 0, s[10:11]
	v_lshl_add_u64 v[78:79], v[46:47], 0, s[10:11]
	v_lshl_add_u64 v[80:81], v[44:45], 0, s[10:11]
	v_lshl_add_u64 v[82:83], v[42:43], 0, s[10:11]
	v_lshl_add_u64 v[84:85], v[40:41], 0, s[10:11]
	global_load_dword v93, v[70:71], off nt
	global_load_dword v94, v[72:73], off nt
	global_load_dword v95, v[74:75], off nt
	global_load_dword v96, v[76:77], off nt
	global_load_dword v97, v[78:79], off nt
	global_load_dword v98, v[80:81], off nt
	global_load_dword v99, v[82:83], off nt
	global_load_dword v100, v[84:85], off nt
	s_add_u32 s10, s10, 0x80800
	s_addc_u32 s11, s11, 0
	v_lshl_add_u64 v[70:71], v[54:55], 0, s[10:11]
	v_lshl_add_u64 v[72:73], v[52:53], 0, s[10:11]
	v_lshl_add_u64 v[74:75], v[50:51], 0, s[10:11]
	v_lshl_add_u64 v[76:77], v[48:49], 0, s[10:11]
	v_lshl_add_u64 v[78:79], v[46:47], 0, s[10:11]
	v_lshl_add_u64 v[80:81], v[44:45], 0, s[10:11]
	v_lshl_add_u64 v[82:83], v[42:43], 0, s[10:11]
	v_lshl_add_u64 v[84:85], v[40:41], 0, s[10:11]
	global_load_dword v101, v[70:71], off nt
	global_load_dword v102, v[72:73], off nt
	global_load_dword v103, v[74:75], off nt
	global_load_dword v104, v[76:77], off nt
	global_load_dword v105, v[78:79], off nt
	global_load_dword v106, v[80:81], off nt
	global_load_dword v107, v[82:83], off nt
	global_load_dword v108, v[84:85], off nt
	s_add_u32 s10, s10, 0x80800
	s_addc_u32 s11, s11, 0
	v_lshl_add_u64 v[70:71], v[54:55], 0, s[10:11]
	v_lshl_add_u64 v[72:73], v[52:53], 0, s[10:11]
	v_lshl_add_u64 v[74:75], v[50:51], 0, s[10:11]
	v_lshl_add_u64 v[76:77], v[48:49], 0, s[10:11]
	v_lshl_add_u64 v[78:79], v[46:47], 0, s[10:11]
	v_lshl_add_u64 v[80:81], v[44:45], 0, s[10:11]
	v_lshl_add_u64 v[82:83], v[42:43], 0, s[10:11]
	v_lshl_add_u64 v[84:85], v[40:41], 0, s[10:11]
	global_load_dword v109, v[70:71], off nt
	global_load_dword v110, v[72:73], off nt
	global_load_dword v111, v[74:75], off nt
	global_load_dword v112, v[76:77], off nt
	global_load_dword v113, v[78:79], off nt
	global_load_dword v114, v[80:81], off nt
	global_load_dword v115, v[82:83], off nt
	global_load_dword v116, v[84:85], off nt
	s_add_u32 s10, s10, 0x80800
	s_addc_u32 s11, s11, 0
	v_lshl_add_u64 v[70:71], v[54:55], 0, s[10:11]
	v_lshl_add_u64 v[72:73], v[52:53], 0, s[10:11]
	v_lshl_add_u64 v[74:75], v[50:51], 0, s[10:11]
	v_lshl_add_u64 v[76:77], v[48:49], 0, s[10:11]
	v_lshl_add_u64 v[78:79], v[46:47], 0, s[10:11]
	v_lshl_add_u64 v[80:81], v[44:45], 0, s[10:11]
	v_lshl_add_u64 v[82:83], v[42:43], 0, s[10:11]
	v_lshl_add_u64 v[84:85], v[40:41], 0, s[10:11]
	global_load_dword v117, v[70:71], off nt
	global_load_dword v118, v[72:73], off nt
	global_load_dword v119, v[74:75], off nt
	global_load_dword v120, v[76:77], off nt
	global_load_dword v121, v[78:79], off nt
	global_load_dword v122, v[80:81], off nt
	global_load_dword v123, v[82:83], off nt
	global_load_dword v124, v[84:85], off nt
	s_add_u32 s10, s10, 0x80800
	s_addc_u32 s11, s11, 0
	v_add_u32_e32 v125, 0x400, v68
	s_waitcnt vmcnt(30)
	ds_write2_b32 v68, v93, v94 offset1:66
	s_waitcnt vmcnt(28)
	ds_write2_b32 v68, v95, v96 offset0:132 offset1:198
	s_waitcnt vmcnt(26)
	ds_write2_b32 v125, v97, v98 offset0:8 offset1:74
	s_waitcnt vmcnt(24)
	ds_write2_b32 v125, v99, v100 offset0:140 offset1:206
	v_add_u32_e32 v68, 0x840, v68
	v_add_u32_e32 v125, 0x400, v68
	s_waitcnt vmcnt(22)
	ds_write2_b32 v68, v101, v102 offset1:66
	s_waitcnt vmcnt(20)
	ds_write2_b32 v68, v103, v104 offset0:132 offset1:198
	s_waitcnt vmcnt(18)
	ds_write2_b32 v125, v105, v106 offset0:8 offset1:74
	s_waitcnt vmcnt(16)
	ds_write2_b32 v125, v107, v108 offset0:140 offset1:206
	v_add_u32_e32 v68, 0x840, v68
	v_add_u32_e32 v125, 0x400, v68
	s_waitcnt vmcnt(14)
	ds_write2_b32 v68, v109, v110 offset1:66
	s_waitcnt vmcnt(12)
	ds_write2_b32 v68, v111, v112 offset0:132 offset1:198
	s_waitcnt vmcnt(10)
	ds_write2_b32 v125, v113, v114 offset0:8 offset1:74
	s_waitcnt vmcnt(8)
	ds_write2_b32 v125, v115, v116 offset0:140 offset1:206
	v_add_u32_e32 v68, 0x840, v68
	v_add_u32_e32 v125, 0x400, v68
	s_waitcnt vmcnt(6)
	ds_write2_b32 v68, v117, v118 offset1:66
	s_waitcnt vmcnt(4)
	ds_write2_b32 v68, v119, v120 offset0:132 offset1:198
	s_waitcnt vmcnt(2)
	ds_write2_b32 v125, v121, v122 offset0:8 offset1:74
	s_waitcnt vmcnt(0)
	ds_write2_b32 v125, v123, v124 offset0:140 offset1:206
	v_add_u32_e32 v68, 0x840, v68
	s_waitcnt lgkmcnt(0)
	ds_read2_b32 v[44:45], v56 offset0:33 offset1:41
	ds_read2_b32 v[46:47], v56 offset1:8
	ds_read2_b32 v[48:49], v56 offset0:66 offset1:74
	ds_read2_b32 v[50:51], v56 offset0:99 offset1:107
	ds_read2_b32 v[52:53], v56 offset0:132 offset1:140
	ds_read2_b32 v[54:55], v56 offset0:165 offset1:173
	ds_read2_b32 v[68:69], v56 offset0:198 offset1:206
	ds_read2_b32 v[70:71], v56 offset0:231 offset1:239
	s_and_b32 s10, 0xffff, s13
	s_and_b32 s0, 0xffff, s12
	v_add_u32_e32 v74, s10, v1
	s_lshl_b32 s0, s0, 1
	v_ashrrev_i32_e32 v75, 31, v74
	v_lshl_add_u64 v[72:73], v[14:15], 0, s[0:1]
	v_lshlrev_b64 v[74:75], 12, v[74:75]
	s_waitcnt lgkmcnt(6)
	v_cvt_pk_bf16_f32 v40, v46, v44
	s_waitcnt lgkmcnt(4)
	v_cvt_pk_bf16_f32 v41, v48, v50
	s_waitcnt lgkmcnt(2)
	v_cvt_pk_bf16_f32 v42, v52, v54
	s_waitcnt lgkmcnt(0)
	v_cvt_pk_bf16_f32 v43, v68, v70
	v_lshl_add_u64 v[74:75], v[72:73], 0, v[74:75]
	v_add_u32_e32 v44, s10, v57
	global_store_dwordx4 v[74:75], v[40:43], off
	s_nop 1
	v_cvt_pk_bf16_f32 v40, v47, v45
	v_ashrrev_i32_e32 v45, 31, v44
	v_cvt_pk_bf16_f32 v41, v49, v51
	v_cvt_pk_bf16_f32 v42, v53, v55
	v_cvt_pk_bf16_f32 v43, v69, v71
	v_lshlrev_b64 v[44:45], 12, v[44:45]
	ds_read2_b32 v[46:47], v56 offset0:49 offset1:57
	ds_read2_b32 v[48:49], v56 offset0:16 offset1:24
	ds_read2_b32 v[50:51], v56 offset0:82 offset1:90
	ds_read2_b32 v[52:53], v56 offset0:115 offset1:123
	ds_read2_b32 v[54:55], v56 offset0:148 offset1:156
	ds_read2_b32 v[68:69], v56 offset0:181 offset1:189
	ds_read2_b32 v[70:71], v56 offset0:214 offset1:222
	ds_read2_b32 v[74:75], v56 offset0:247 offset1:255
	v_lshl_add_u64 v[44:45], v[72:73], 0, v[44:45]
	global_store_dwordx4 v[44:45], v[40:43], off
	v_add_u32_e32 v44, s10, v58
	v_ashrrev_i32_e32 v45, 31, v44
	v_lshlrev_b64 v[44:45], 12, v[44:45]
	s_waitcnt lgkmcnt(6)
	v_cvt_pk_bf16_f32 v40, v48, v46
	s_waitcnt lgkmcnt(4)
	v_cvt_pk_bf16_f32 v41, v50, v52
	s_waitcnt lgkmcnt(2)
	v_cvt_pk_bf16_f32 v42, v54, v68
	s_waitcnt lgkmcnt(0)
	v_cvt_pk_bf16_f32 v43, v70, v74
	v_lshl_add_u64 v[44:45], v[72:73], 0, v[44:45]
	global_store_dwordx4 v[44:45], v[40:43], off
	v_add_u32_e32 v44, s10, v59
	v_ashrrev_i32_e32 v45, 31, v44
	v_lshlrev_b64 v[44:45], 12, v[44:45]
	v_cvt_pk_bf16_f32 v40, v49, v47
	v_cvt_pk_bf16_f32 v41, v51, v53
	v_cvt_pk_bf16_f32 v42, v55, v69
	v_cvt_pk_bf16_f32 v43, v71, v75
	v_lshl_add_u64 v[44:45], v[72:73], 0, v[44:45]
	global_store_dwordx4 v[44:45], v[40:43], off
	s_waitcnt lgkmcnt(0)

.LBB0_55:
	v_lshl_add_u64 v[70:71], v[54:55], 0, s[10:11]
	v_lshl_add_u64 v[72:73], v[52:53], 0, s[10:11]
	v_lshl_add_u64 v[74:75], v[50:51], 0, s[10:11]
	v_lshl_add_u64 v[76:77], v[48:49], 0, s[10:11]
	v_lshl_add_u64 v[78:79], v[46:47], 0, s[10:11]
	v_lshl_add_u64 v[80:81], v[44:45], 0, s[10:11]
	v_lshl_add_u64 v[82:83], v[42:43], 0, s[10:11]
	v_lshl_add_u64 v[84:85], v[40:41], 0, s[10:11]
	global_load_dword v93, v[70:71], off nt
	global_load_dword v94, v[72:73], off nt
	global_load_dword v95, v[74:75], off nt
	global_load_dword v96, v[76:77], off nt
	global_load_dword v97, v[78:79], off nt
	global_load_dword v98, v[80:81], off nt
	global_load_dword v99, v[82:83], off nt
	global_load_dword v100, v[84:85], off nt
	s_add_u32 s10, s10, 0x80000
	s_addc_u32 s11, s11, 0
	v_lshl_add_u64 v[70:71], v[54:55], 0, s[10:11]
	v_lshl_add_u64 v[72:73], v[52:53], 0, s[10:11]
	v_lshl_add_u64 v[74:75], v[50:51], 0, s[10:11]
	v_lshl_add_u64 v[76:77], v[48:49], 0, s[10:11]
	v_lshl_add_u64 v[78:79], v[46:47], 0, s[10:11]
	v_lshl_add_u64 v[80:81], v[44:45], 0, s[10:11]
	v_lshl_add_u64 v[82:83], v[42:43], 0, s[10:11]
	v_lshl_add_u64 v[84:85], v[40:41], 0, s[10:11]
	global_load_dword v101, v[70:71], off nt
	global_load_dword v102, v[72:73], off nt
	global_load_dword v103, v[74:75], off nt
	global_load_dword v104, v[76:77], off nt
	global_load_dword v105, v[78:79], off nt
	global_load_dword v106, v[80:81], off nt
	global_load_dword v107, v[82:83], off nt
	global_load_dword v108, v[84:85], off nt
	s_add_u32 s10, s10, 0x80000
	s_addc_u32 s11, s11, 0
	v_lshl_add_u64 v[70:71], v[54:55], 0, s[10:11]
	v_lshl_add_u64 v[72:73], v[52:53], 0, s[10:11]
	v_lshl_add_u64 v[74:75], v[50:51], 0, s[10:11]
	v_lshl_add_u64 v[76:77], v[48:49], 0, s[10:11]
	v_lshl_add_u64 v[78:79], v[46:47], 0, s[10:11]
	v_lshl_add_u64 v[80:81], v[44:45], 0, s[10:11]
	v_lshl_add_u64 v[82:83], v[42:43], 0, s[10:11]
	v_lshl_add_u64 v[84:85], v[40:41], 0, s[10:11]
	global_load_dword v109, v[70:71], off nt
	global_load_dword v110, v[72:73], off nt
	global_load_dword v111, v[74:75], off nt
	global_load_dword v112, v[76:77], off nt
	global_load_dword v113, v[78:79], off nt
	global_load_dword v114, v[80:81], off nt
	global_load_dword v115, v[82:83], off nt
	global_load_dword v116, v[84:85], off nt
	s_add_u32 s10, s10, 0x80000
	s_addc_u32 s11, s11, 0
	v_lshl_add_u64 v[70:71], v[54:55], 0, s[10:11]
	v_lshl_add_u64 v[72:73], v[52:53], 0, s[10:11]
	v_lshl_add_u64 v[74:75], v[50:51], 0, s[10:11]
	v_lshl_add_u64 v[76:77], v[48:49], 0, s[10:11]
	v_lshl_add_u64 v[78:79], v[46:47], 0, s[10:11]
	v_lshl_add_u64 v[80:81], v[44:45], 0, s[10:11]
	v_lshl_add_u64 v[82:83], v[42:43], 0, s[10:11]
	v_lshl_add_u64 v[84:85], v[40:41], 0, s[10:11]
	global_load_dword v117, v[70:71], off nt
	global_load_dword v118, v[72:73], off nt
	global_load_dword v119, v[74:75], off nt
	global_load_dword v120, v[76:77], off nt
	global_load_dword v121, v[78:79], off nt
	global_load_dword v122, v[80:81], off nt
	global_load_dword v123, v[82:83], off nt
	global_load_dword v124, v[84:85], off nt
	s_add_u32 s10, s10, 0x80000
	s_addc_u32 s11, s11, 0
	v_add_u32_e32 v125, 0x400, v68
	s_waitcnt vmcnt(30)
	ds_write2_b32 v68, v93, v94 offset1:66
	s_waitcnt vmcnt(28)
	ds_write2_b32 v68, v95, v96 offset0:132 offset1:198
	s_waitcnt vmcnt(26)
	ds_write2_b32 v125, v97, v98 offset0:8 offset1:74
	s_waitcnt vmcnt(24)
	ds_write2_b32 v125, v99, v100 offset0:140 offset1:206
	v_add_u32_e32 v68, 0x840, v68
	v_add_u32_e32 v125, 0x400, v68
	s_waitcnt vmcnt(22)
	ds_write2_b32 v68, v101, v102 offset1:66
	s_waitcnt vmcnt(20)
	ds_write2_b32 v68, v103, v104 offset0:132 offset1:198
	s_waitcnt vmcnt(18)
	ds_write2_b32 v125, v105, v106 offset0:8 offset1:74
	s_waitcnt vmcnt(16)
	ds_write2_b32 v125, v107, v108 offset0:140 offset1:206
	v_add_u32_e32 v68, 0x840, v68
	v_add_u32_e32 v125, 0x400, v68
	s_waitcnt vmcnt(14)
	ds_write2_b32 v68, v109, v110 offset1:66
	s_waitcnt vmcnt(12)
	ds_write2_b32 v68, v111, v112 offset0:132 offset1:198
	s_waitcnt vmcnt(10)
	ds_write2_b32 v125, v113, v114 offset0:8 offset1:74
	s_waitcnt vmcnt(8)
	ds_write2_b32 v125, v115, v116 offset0:140 offset1:206
	v_add_u32_e32 v68, 0x840, v68
	v_add_u32_e32 v125, 0x400, v68
	s_waitcnt vmcnt(6)
	ds_write2_b32 v68, v117, v118 offset1:66
	s_waitcnt vmcnt(4)
	ds_write2_b32 v68, v119, v120 offset0:132 offset1:198
	s_waitcnt vmcnt(2)
	ds_write2_b32 v125, v121, v122 offset0:8 offset1:74
	s_waitcnt vmcnt(0)
	ds_write2_b32 v125, v123, v124 offset0:140 offset1:206
	v_add_u32_e32 v68, 0x840, v68
	s_waitcnt lgkmcnt(0)
	s_lshl_b32 s10, s27, 5
	ds_read2_b32 v[44:45], v56 offset0:33 offset1:41
	ds_read2_b32 v[46:47], v56 offset1:8
	ds_read2_b32 v[48:49], v56 offset0:66 offset1:74
	ds_read2_b32 v[50:51], v56 offset0:99 offset1:107
	ds_read2_b32 v[52:53], v56 offset0:132 offset1:140
	ds_read2_b32 v[54:55], v56 offset0:165 offset1:173
	ds_read2_b32 v[68:69], v56 offset0:198 offset1:206
	ds_read2_b32 v[70:71], v56 offset0:231 offset1:239
	s_add_i32 s0, s27, 0xdc00
	s_and_b32 s10, s10, 0x1fe0
	s_bfe_u32 s0, s0, 0x80008
	v_add_u32_e32 v74, s10, v1
	s_lshl_b32 s0, s0, 7
	v_ashrrev_i32_e32 v75, 31, v74
	v_lshl_add_u64 v[72:73], v[16:17], 0, s[0:1]
	v_lshlrev_b64 v[74:75], 12, v[74:75]
	s_waitcnt lgkmcnt(6)
	v_cvt_pk_bf16_f32 v40, v46, v44
	s_waitcnt lgkmcnt(4)
	v_cvt_pk_bf16_f32 v41, v48, v50
	s_waitcnt lgkmcnt(2)
	v_cvt_pk_bf16_f32 v42, v52, v54
	s_waitcnt lgkmcnt(0)
	v_cvt_pk_bf16_f32 v43, v68, v70
	v_lshl_add_u64 v[74:75], v[72:73], 0, v[74:75]
	v_add_u32_e32 v44, s10, v57
	global_store_dwordx4 v[74:75], v[40:43], off
	s_nop 1
	v_cvt_pk_bf16_f32 v40, v47, v45
	v_ashrrev_i32_e32 v45, 31, v44
	v_cvt_pk_bf16_f32 v41, v49, v51
	v_cvt_pk_bf16_f32 v42, v53, v55
	v_cvt_pk_bf16_f32 v43, v69, v71
	v_lshlrev_b64 v[44:45], 12, v[44:45]
	ds_read2_b32 v[46:47], v56 offset0:49 offset1:57
	ds_read2_b32 v[48:49], v56 offset0:16 offset1:24
	ds_read2_b32 v[50:51], v56 offset0:82 offset1:90
	ds_read2_b32 v[52:53], v56 offset0:115 offset1:123
	ds_read2_b32 v[54:55], v56 offset0:148 offset1:156
	ds_read2_b32 v[68:69], v56 offset0:181 offset1:189
	ds_read2_b32 v[70:71], v56 offset0:214 offset1:222
	ds_read2_b32 v[74:75], v56 offset0:247 offset1:255
	v_lshl_add_u64 v[44:45], v[72:73], 0, v[44:45]
	global_store_dwordx4 v[44:45], v[40:43], off
	v_add_u32_e32 v44, s10, v58
	v_ashrrev_i32_e32 v45, 31, v44
	v_lshlrev_b64 v[44:45], 12, v[44:45]
	s_waitcnt lgkmcnt(6)
	v_cvt_pk_bf16_f32 v40, v48, v46
	s_waitcnt lgkmcnt(4)
	v_cvt_pk_bf16_f32 v41, v50, v52
	s_waitcnt lgkmcnt(2)
	v_cvt_pk_bf16_f32 v42, v54, v68
	s_waitcnt lgkmcnt(0)
	v_cvt_pk_bf16_f32 v43, v70, v74
	v_lshl_add_u64 v[44:45], v[72:73], 0, v[44:45]
	global_store_dwordx4 v[44:45], v[40:43], off
	v_add_u32_e32 v44, s10, v59
	v_ashrrev_i32_e32 v45, 31, v44
	v_lshlrev_b64 v[44:45], 12, v[44:45]
	v_cvt_pk_bf16_f32 v40, v49, v47
	v_cvt_pk_bf16_f32 v41, v51, v53
	v_cvt_pk_bf16_f32 v42, v55, v69
	v_cvt_pk_bf16_f32 v43, v71, v75
	v_lshl_add_u64 v[44:45], v[72:73], 0, v[44:45]
	global_store_dwordx4 v[44:45], v[40:43], off
	s_waitcnt lgkmcnt(0)

.LBB0_60:
	v_lshl_add_u64 v[70:71], v[54:55], 0, s[10:11]
	v_lshl_add_u64 v[72:73], v[52:53], 0, s[10:11]
	v_lshl_add_u64 v[74:75], v[50:51], 0, s[10:11]
	v_lshl_add_u64 v[76:77], v[48:49], 0, s[10:11]
	v_lshl_add_u64 v[78:79], v[46:47], 0, s[10:11]
	v_lshl_add_u64 v[80:81], v[44:45], 0, s[10:11]
	v_lshl_add_u64 v[82:83], v[42:43], 0, s[10:11]
	v_lshl_add_u64 v[84:85], v[40:41], 0, s[10:11]
	global_load_dword v93, v[70:71], off nt
	global_load_dword v94, v[72:73], off nt
	global_load_dword v95, v[74:75], off nt
	global_load_dword v96, v[76:77], off nt
	global_load_dword v97, v[78:79], off nt
	global_load_dword v98, v[80:81], off nt
	global_load_dword v99, v[82:83], off nt
	global_load_dword v100, v[84:85], off nt
	s_add_u32 s10, s10, 0x48000
	s_addc_u32 s11, s11, 0
	v_lshl_add_u64 v[70:71], v[54:55], 0, s[10:11]
	v_lshl_add_u64 v[72:73], v[52:53], 0, s[10:11]
	v_lshl_add_u64 v[74:75], v[50:51], 0, s[10:11]
	v_lshl_add_u64 v[76:77], v[48:49], 0, s[10:11]
	v_lshl_add_u64 v[78:79], v[46:47], 0, s[10:11]
	v_lshl_add_u64 v[80:81], v[44:45], 0, s[10:11]
	v_lshl_add_u64 v[82:83], v[42:43], 0, s[10:11]
	v_lshl_add_u64 v[84:85], v[40:41], 0, s[10:11]
	global_load_dword v101, v[70:71], off nt
	global_load_dword v102, v[72:73], off nt
	global_load_dword v103, v[74:75], off nt
	global_load_dword v104, v[76:77], off nt
	global_load_dword v105, v[78:79], off nt
	global_load_dword v106, v[80:81], off nt
	global_load_dword v107, v[82:83], off nt
	global_load_dword v108, v[84:85], off nt
	s_add_u32 s10, s10, 0x48000
	s_addc_u32 s11, s11, 0
	v_lshl_add_u64 v[70:71], v[54:55], 0, s[10:11]
	v_lshl_add_u64 v[72:73], v[52:53], 0, s[10:11]
	v_lshl_add_u64 v[74:75], v[50:51], 0, s[10:11]
	v_lshl_add_u64 v[76:77], v[48:49], 0, s[10:11]
	v_lshl_add_u64 v[78:79], v[46:47], 0, s[10:11]
	v_lshl_add_u64 v[80:81], v[44:45], 0, s[10:11]
	v_lshl_add_u64 v[82:83], v[42:43], 0, s[10:11]
	v_lshl_add_u64 v[84:85], v[40:41], 0, s[10:11]
	global_load_dword v109, v[70:71], off nt
	global_load_dword v110, v[72:73], off nt
	global_load_dword v111, v[74:75], off nt
	global_load_dword v112, v[76:77], off nt
	global_load_dword v113, v[78:79], off nt
	global_load_dword v114, v[80:81], off nt
	global_load_dword v115, v[82:83], off nt
	global_load_dword v116, v[84:85], off nt
	s_add_u32 s10, s10, 0x48000
	s_addc_u32 s11, s11, 0
	v_lshl_add_u64 v[70:71], v[54:55], 0, s[10:11]
	v_lshl_add_u64 v[72:73], v[52:53], 0, s[10:11]
	v_lshl_add_u64 v[74:75], v[50:51], 0, s[10:11]
	v_lshl_add_u64 v[76:77], v[48:49], 0, s[10:11]
	v_lshl_add_u64 v[78:79], v[46:47], 0, s[10:11]
	v_lshl_add_u64 v[80:81], v[44:45], 0, s[10:11]
	v_lshl_add_u64 v[82:83], v[42:43], 0, s[10:11]
	v_lshl_add_u64 v[84:85], v[40:41], 0, s[10:11]
	global_load_dword v117, v[70:71], off nt
	global_load_dword v118, v[72:73], off nt
	global_load_dword v119, v[74:75], off nt
	global_load_dword v120, v[76:77], off nt
	global_load_dword v121, v[78:79], off nt
	global_load_dword v122, v[80:81], off nt
	global_load_dword v123, v[82:83], off nt
	global_load_dword v124, v[84:85], off nt
	s_add_u32 s10, s10, 0x48000
	s_addc_u32 s11, s11, 0
	v_add_u32_e32 v125, 0x400, v68
	s_waitcnt vmcnt(30)
	ds_write2_b32 v68, v93, v94 offset1:66
	s_waitcnt vmcnt(28)
	ds_write2_b32 v68, v95, v96 offset0:132 offset1:198
	s_waitcnt vmcnt(26)
	ds_write2_b32 v125, v97, v98 offset0:8 offset1:74
	s_waitcnt vmcnt(24)
	ds_write2_b32 v125, v99, v100 offset0:140 offset1:206
	v_add_u32_e32 v68, 0x840, v68
	v_add_u32_e32 v125, 0x400, v68
	s_waitcnt vmcnt(22)
	ds_write2_b32 v68, v101, v102 offset1:66
	s_waitcnt vmcnt(20)
	ds_write2_b32 v68, v103, v104 offset0:132 offset1:198
	s_waitcnt vmcnt(18)
	ds_write2_b32 v125, v105, v106 offset0:8 offset1:74
	s_waitcnt vmcnt(16)
	ds_write2_b32 v125, v107, v108 offset0:140 offset1:206
	v_add_u32_e32 v68, 0x840, v68
	v_add_u32_e32 v125, 0x400, v68
	s_waitcnt vmcnt(14)
	ds_write2_b32 v68, v109, v110 offset1:66
	s_waitcnt vmcnt(12)
	ds_write2_b32 v68, v111, v112 offset0:132 offset1:198
	s_waitcnt vmcnt(10)
	ds_write2_b32 v125, v113, v114 offset0:8 offset1:74
	s_waitcnt vmcnt(8)
	ds_write2_b32 v125, v115, v116 offset0:140 offset1:206
	v_add_u32_e32 v68, 0x840, v68
	v_add_u32_e32 v125, 0x400, v68
	s_waitcnt vmcnt(6)
	ds_write2_b32 v68, v117, v118 offset1:66
	s_waitcnt vmcnt(4)
	ds_write2_b32 v68, v119, v120 offset0:132 offset1:198
	s_waitcnt vmcnt(2)
	ds_write2_b32 v125, v121, v122 offset0:8 offset1:74
	s_waitcnt vmcnt(0)
	ds_write2_b32 v125, v123, v124 offset0:140 offset1:206
	v_add_u32_e32 v68, 0x840, v68
	s_waitcnt lgkmcnt(0)
	ds_read2_b32 v[44:45], v56 offset0:33 offset1:41
	ds_read2_b32 v[46:47], v56 offset1:8
	ds_read2_b32 v[48:49], v56 offset0:66 offset1:74
	ds_read2_b32 v[50:51], v56 offset0:99 offset1:107
	ds_read2_b32 v[52:53], v56 offset0:132 offset1:140
	ds_read2_b32 v[54:55], v56 offset0:165 offset1:173
	ds_read2_b32 v[68:69], v56 offset0:198 offset1:206
	ds_read2_b32 v[70:71], v56 offset0:231 offset1:239
	s_and_b32 s10, 0xffff, s13
	s_and_b32 s0, 0xffff, s12
	v_add_u32_e32 v74, s10, v1
	s_lshl_b32 s0, s0, 1
	v_ashrrev_i32_e32 v75, 31, v74
	v_lshl_add_u64 v[72:73], v[18:19], 0, s[0:1]
	v_lshlrev_b64 v[74:75], 12, v[74:75]
	s_waitcnt lgkmcnt(6)
	v_cvt_pk_bf16_f32 v40, v46, v44
	s_waitcnt lgkmcnt(4)
	v_cvt_pk_bf16_f32 v41, v48, v50
	s_waitcnt lgkmcnt(2)
	v_cvt_pk_bf16_f32 v42, v52, v54
	s_waitcnt lgkmcnt(0)
	v_cvt_pk_bf16_f32 v43, v68, v70
	v_lshl_add_u64 v[74:75], v[72:73], 0, v[74:75]
	v_add_u32_e32 v44, s10, v57
	global_store_dwordx4 v[74:75], v[40:43], off
	s_nop 1
	v_cvt_pk_bf16_f32 v40, v47, v45
	v_ashrrev_i32_e32 v45, 31, v44
	v_cvt_pk_bf16_f32 v41, v49, v51
	v_cvt_pk_bf16_f32 v42, v53, v55
	v_cvt_pk_bf16_f32 v43, v69, v71
	v_lshlrev_b64 v[44:45], 12, v[44:45]
	ds_read2_b32 v[46:47], v56 offset0:49 offset1:57
	ds_read2_b32 v[48:49], v56 offset0:16 offset1:24
	ds_read2_b32 v[50:51], v56 offset0:82 offset1:90
	ds_read2_b32 v[52:53], v56 offset0:115 offset1:123
	ds_read2_b32 v[54:55], v56 offset0:148 offset1:156
	ds_read2_b32 v[68:69], v56 offset0:181 offset1:189
	ds_read2_b32 v[70:71], v56 offset0:214 offset1:222
	ds_read2_b32 v[74:75], v56 offset0:247 offset1:255
	v_lshl_add_u64 v[44:45], v[72:73], 0, v[44:45]
	global_store_dwordx4 v[44:45], v[40:43], off
	v_add_u32_e32 v44, s10, v58
	v_ashrrev_i32_e32 v45, 31, v44
	v_lshlrev_b64 v[44:45], 12, v[44:45]
	s_waitcnt lgkmcnt(6)
	v_cvt_pk_bf16_f32 v40, v48, v46
	s_waitcnt lgkmcnt(4)
	v_cvt_pk_bf16_f32 v41, v50, v52
	s_waitcnt lgkmcnt(2)
	v_cvt_pk_bf16_f32 v42, v54, v68
	s_waitcnt lgkmcnt(0)
	v_cvt_pk_bf16_f32 v43, v70, v74
	v_lshl_add_u64 v[44:45], v[72:73], 0, v[44:45]
	global_store_dwordx4 v[44:45], v[40:43], off
	v_add_u32_e32 v44, s10, v59
	v_ashrrev_i32_e32 v45, 31, v44
	v_lshlrev_b64 v[44:45], 12, v[44:45]
	v_cvt_pk_bf16_f32 v40, v49, v47
	v_cvt_pk_bf16_f32 v41, v51, v53
	v_cvt_pk_bf16_f32 v42, v55, v69
	v_cvt_pk_bf16_f32 v43, v71, v75
	v_lshl_add_u64 v[44:45], v[72:73], 0, v[44:45]
	global_store_dwordx4 v[44:45], v[40:43], off
	s_waitcnt lgkmcnt(0)

.LBB0_65:
	v_lshl_add_u64 v[70:71], v[54:55], 0, s[14:15]
	v_lshl_add_u64 v[72:73], v[52:53], 0, s[14:15]
	v_lshl_add_u64 v[74:75], v[50:51], 0, s[14:15]
	v_lshl_add_u64 v[76:77], v[48:49], 0, s[14:15]
	v_lshl_add_u64 v[78:79], v[46:47], 0, s[14:15]
	v_lshl_add_u64 v[80:81], v[44:45], 0, s[14:15]
	v_lshl_add_u64 v[82:83], v[42:43], 0, s[14:15]
	v_lshl_add_u64 v[84:85], v[40:41], 0, s[14:15]
	global_load_dword v93, v[70:71], off nt
	global_load_dword v94, v[72:73], off nt
	global_load_dword v95, v[74:75], off nt
	global_load_dword v96, v[76:77], off nt
	global_load_dword v97, v[78:79], off nt
	global_load_dword v98, v[80:81], off nt
	global_load_dword v99, v[82:83], off nt
	global_load_dword v100, v[84:85], off nt
	s_add_u32 s14, s14, 0x48000
	s_addc_u32 s15, s15, 0
	v_lshl_add_u64 v[70:71], v[54:55], 0, s[14:15]
	v_lshl_add_u64 v[72:73], v[52:53], 0, s[14:15]
	v_lshl_add_u64 v[74:75], v[50:51], 0, s[14:15]
	v_lshl_add_u64 v[76:77], v[48:49], 0, s[14:15]
	v_lshl_add_u64 v[78:79], v[46:47], 0, s[14:15]
	v_lshl_add_u64 v[80:81], v[44:45], 0, s[14:15]
	v_lshl_add_u64 v[82:83], v[42:43], 0, s[14:15]
	v_lshl_add_u64 v[84:85], v[40:41], 0, s[14:15]
	global_load_dword v101, v[70:71], off nt
	global_load_dword v102, v[72:73], off nt
	global_load_dword v103, v[74:75], off nt
	global_load_dword v104, v[76:77], off nt
	global_load_dword v105, v[78:79], off nt
	global_load_dword v106, v[80:81], off nt
	global_load_dword v107, v[82:83], off nt
	global_load_dword v108, v[84:85], off nt
	s_add_u32 s14, s14, 0x48000
	s_addc_u32 s15, s15, 0
	v_lshl_add_u64 v[70:71], v[54:55], 0, s[14:15]
	v_lshl_add_u64 v[72:73], v[52:53], 0, s[14:15]
	v_lshl_add_u64 v[74:75], v[50:51], 0, s[14:15]
	v_lshl_add_u64 v[76:77], v[48:49], 0, s[14:15]
	v_lshl_add_u64 v[78:79], v[46:47], 0, s[14:15]
	v_lshl_add_u64 v[80:81], v[44:45], 0, s[14:15]
	v_lshl_add_u64 v[82:83], v[42:43], 0, s[14:15]
	v_lshl_add_u64 v[84:85], v[40:41], 0, s[14:15]
	global_load_dword v109, v[70:71], off nt
	global_load_dword v110, v[72:73], off nt
	global_load_dword v111, v[74:75], off nt
	global_load_dword v112, v[76:77], off nt
	global_load_dword v113, v[78:79], off nt
	global_load_dword v114, v[80:81], off nt
	global_load_dword v115, v[82:83], off nt
	global_load_dword v116, v[84:85], off nt
	s_add_u32 s14, s14, 0x48000
	s_addc_u32 s15, s15, 0
	v_lshl_add_u64 v[70:71], v[54:55], 0, s[14:15]
	v_lshl_add_u64 v[72:73], v[52:53], 0, s[14:15]
	v_lshl_add_u64 v[74:75], v[50:51], 0, s[14:15]
	v_lshl_add_u64 v[76:77], v[48:49], 0, s[14:15]
	v_lshl_add_u64 v[78:79], v[46:47], 0, s[14:15]
	v_lshl_add_u64 v[80:81], v[44:45], 0, s[14:15]
	v_lshl_add_u64 v[82:83], v[42:43], 0, s[14:15]
	v_lshl_add_u64 v[84:85], v[40:41], 0, s[14:15]
	global_load_dword v117, v[70:71], off nt
	global_load_dword v118, v[72:73], off nt
	global_load_dword v119, v[74:75], off nt
	global_load_dword v120, v[76:77], off nt
	global_load_dword v121, v[78:79], off nt
	global_load_dword v122, v[80:81], off nt
	global_load_dword v123, v[82:83], off nt
	global_load_dword v124, v[84:85], off nt
	s_add_u32 s14, s14, 0x48000
	s_addc_u32 s15, s15, 0
	v_add_u32_e32 v125, 0x400, v68
	s_waitcnt vmcnt(30)
	ds_write2_b32 v68, v93, v94 offset1:66
	s_waitcnt vmcnt(28)
	ds_write2_b32 v68, v95, v96 offset0:132 offset1:198
	s_waitcnt vmcnt(26)
	ds_write2_b32 v125, v97, v98 offset0:8 offset1:74
	s_waitcnt vmcnt(24)
	ds_write2_b32 v125, v99, v100 offset0:140 offset1:206
	v_add_u32_e32 v68, 0x840, v68
	v_add_u32_e32 v125, 0x400, v68
	s_waitcnt vmcnt(22)
	ds_write2_b32 v68, v101, v102 offset1:66
	s_waitcnt vmcnt(20)
	ds_write2_b32 v68, v103, v104 offset0:132 offset1:198
	s_waitcnt vmcnt(18)
	ds_write2_b32 v125, v105, v106 offset0:8 offset1:74
	s_waitcnt vmcnt(16)
	ds_write2_b32 v125, v107, v108 offset0:140 offset1:206
	v_add_u32_e32 v68, 0x840, v68
	v_add_u32_e32 v125, 0x400, v68
	s_waitcnt vmcnt(14)
	ds_write2_b32 v68, v109, v110 offset1:66
	s_waitcnt vmcnt(12)
	ds_write2_b32 v68, v111, v112 offset0:132 offset1:198
	s_waitcnt vmcnt(10)
	ds_write2_b32 v125, v113, v114 offset0:8 offset1:74
	s_waitcnt vmcnt(8)
	ds_write2_b32 v125, v115, v116 offset0:140 offset1:206
	v_add_u32_e32 v68, 0x840, v68
	v_add_u32_e32 v125, 0x400, v68
	s_waitcnt vmcnt(6)
	ds_write2_b32 v68, v117, v118 offset1:66
	s_waitcnt vmcnt(4)
	ds_write2_b32 v68, v119, v120 offset0:132 offset1:198
	s_waitcnt vmcnt(2)
	ds_write2_b32 v125, v121, v122 offset0:8 offset1:74
	s_waitcnt vmcnt(0)
	ds_write2_b32 v125, v123, v124 offset0:140 offset1:206
	v_add_u32_e32 v68, 0x840, v68
	s_waitcnt lgkmcnt(0)
	ds_read2_b32 v[44:45], v56 offset0:33 offset1:41
	ds_read2_b32 v[46:47], v56 offset1:8
	ds_read2_b32 v[48:49], v56 offset0:66 offset1:74
	ds_read2_b32 v[50:51], v56 offset0:99 offset1:107
	ds_read2_b32 v[52:53], v56 offset0:132 offset1:140
	ds_read2_b32 v[54:55], v56 offset0:165 offset1:173
	ds_read2_b32 v[68:69], v56 offset0:198 offset1:206
	ds_read2_b32 v[70:71], v56 offset0:231 offset1:239
	v_add_u32_e32 v74, s10, v1
	v_ashrrev_i32_e32 v75, 31, v74
	v_lshl_add_u64 v[72:73], s[12:13], 1, v[4:5]
	v_lshlrev_b64 v[74:75], 12, v[74:75]
	s_waitcnt lgkmcnt(6)
	v_cvt_pk_bf16_f32 v40, v46, v44
	s_waitcnt lgkmcnt(4)
	v_cvt_pk_bf16_f32 v41, v48, v50
	s_waitcnt lgkmcnt(2)
	v_cvt_pk_bf16_f32 v42, v52, v54
	s_waitcnt lgkmcnt(0)
	v_cvt_pk_bf16_f32 v43, v68, v70
	v_lshl_add_u64 v[74:75], v[72:73], 0, v[74:75]
	v_add_u32_e32 v44, s10, v57
	global_store_dwordx4 v[74:75], v[40:43], off
	s_nop 1
	v_cvt_pk_bf16_f32 v40, v47, v45
	v_ashrrev_i32_e32 v45, 31, v44
	v_cvt_pk_bf16_f32 v41, v49, v51
	v_cvt_pk_bf16_f32 v42, v53, v55
	v_cvt_pk_bf16_f32 v43, v69, v71
	v_lshlrev_b64 v[44:45], 12, v[44:45]
	ds_read2_b32 v[46:47], v56 offset0:49 offset1:57
	ds_read2_b32 v[48:49], v56 offset0:16 offset1:24
	ds_read2_b32 v[50:51], v56 offset0:82 offset1:90
	ds_read2_b32 v[52:53], v56 offset0:115 offset1:123
	ds_read2_b32 v[54:55], v56 offset0:148 offset1:156
	ds_read2_b32 v[68:69], v56 offset0:181 offset1:189
	ds_read2_b32 v[70:71], v56 offset0:214 offset1:222
	ds_read2_b32 v[74:75], v56 offset0:247 offset1:255
	v_lshl_add_u64 v[44:45], v[72:73], 0, v[44:45]
	global_store_dwordx4 v[44:45], v[40:43], off
	v_add_u32_e32 v44, s10, v58
	v_ashrrev_i32_e32 v45, 31, v44
	v_lshlrev_b64 v[44:45], 12, v[44:45]
	s_waitcnt lgkmcnt(6)
	v_cvt_pk_bf16_f32 v40, v48, v46
	s_waitcnt lgkmcnt(4)
	v_cvt_pk_bf16_f32 v41, v50, v52
	s_waitcnt lgkmcnt(2)
	v_cvt_pk_bf16_f32 v42, v54, v68
	s_waitcnt lgkmcnt(0)
	v_cvt_pk_bf16_f32 v43, v70, v74
	v_lshl_add_u64 v[44:45], v[72:73], 0, v[44:45]
	global_store_dwordx4 v[44:45], v[40:43], off
	v_add_u32_e32 v44, s10, v59
	v_ashrrev_i32_e32 v45, 31, v44
	v_lshlrev_b64 v[44:45], 12, v[44:45]
	v_cvt_pk_bf16_f32 v40, v49, v47
	v_cvt_pk_bf16_f32 v41, v51, v53
	v_cvt_pk_bf16_f32 v42, v55, v69
	v_cvt_pk_bf16_f32 v43, v71, v75
	v_lshl_add_u64 v[44:45], v[72:73], 0, v[44:45]
	global_store_dwordx4 v[44:45], v[40:43], off
	s_waitcnt lgkmcnt(0)
	s_branch .LBB0_22
